# ssm_b set-up: 8 C-fragment loads issued at once instead of 4 serialized pairs
# baseline (speedup 1.0000x reference)
.LBB0_184:
	s_or_b64 exec, exec, s[0:1]
	s_waitcnt vmcnt(0)
	v_mul_f32_e32 v28, v10, v18
	v_mul_f32_e32 v0, 0x3fb8aa3b, v28
	s_mov_b32 s0, 0x3fb8aa3b
	v_fma_f32 v18, v28, s0, -v0
	v_rndne_f32_e32 v29, v0
	v_fmac_f32_e32 v18, 0x32a5705f, v28
	v_sub_f32_e32 v0, v0, v29
	v_add_f32_e32 v0, v0, v18
	v_cvt_i32_f32_e32 v30, v29
	v_exp_f32_e32 v0, v0
	s_mov_b32 s0, 0xc2ce8ed0
	v_cmp_ngt_f32_e32 vcc, s0, v28
	s_mov_b32 s0, 0x42b17218
	v_ldexp_f32 v0, v0, v30
	v_cndmask_b32_e32 v0, 0, v0, vcc
	v_cmp_nlt_f32_e32 vcc, s0, v28
	s_movk_i32 s3, 0x1f8
	s_load_dwordx2 s[0:1], s[80:81], 0x78
	v_cmp_class_f32_e64 s[40:41], v16, s3
	v_xor_b32_e32 v16, v17, v16
	v_and_b32_e32 v17, 1, v20
	v_cndmask_b32_e32 v0, v196, v0, vcc
	v_cmp_eq_u32_e32 vcc, 0, v17
	v_mul_f32_e32 v17, v19, v19
	v_fmamk_f32 v18, v17, 0xb94c1982, v191
	v_lshlrev_b32_e32 v20, 30, v20
	v_fmaak_f32 v18, v17, v18, 0xbe2aaa9d
	v_and_b32_e32 v45, 0x80000000, v20
	v_mul_f32_e32 v20, v21, v21
	v_lshlrev_b64 v[12:13], 6, v[12:13]
	v_mul_f32_e32 v18, v17, v18
	v_lshl_add_u64 v[36:37], s[78:79], 0, v[12:13]
	s_waitcnt lgkmcnt(0)
	v_lshl_add_u64 v[40:41], s[0:1], 0, v[12:13]
	v_fmamk_f32 v12, v20, 0xb94c1982, v191
	v_fmac_f32_e32 v19, v19, v18
	v_fmamk_f32 v18, v17, 0x37d75334, v192
	v_fmaak_f32 v12, v20, v12, 0xbe2aaa9d
	v_fmaak_f32 v18, v17, v18, 0x3d2aabf7
	v_mul_f32_e32 v12, v20, v12
	v_fmaak_f32 v18, v17, v18, 0xbf000004
	v_fmac_f32_e32 v21, v21, v12
	v_fmamk_f32 v12, v20, 0x37d75334, v192
	v_fma_f32 v17, v17, v18, 1.0
	v_fmaak_f32 v12, v20, v12, 0x3d2aabf7
	v_cndmask_b32_e32 v18, v17, v19, vcc
	v_fmaak_f32 v12, v20, v12, 0xbf000004
	v_xor_b32_e32 v46, v16, v18
	v_xor_b32_e32 v16, 0x80000000, v19
	v_fma_f32 v12, v20, v12, 1.0
	v_lshlrev_b32_e32 v13, 30, v22
	v_and_b32_e32 v20, 1, v22
	v_cndmask_b32_e32 v47, v16, v17, vcc
	v_and_b32_e32 v13, 0x80000000, v13
	v_cmp_eq_u32_e32 vcc, 0, v20
	v_xor_b32_e32 v15, v15, v14
	v_xor_b32_e32 v13, v15, v13
	v_cndmask_b32_e32 v12, v12, v21, vcc
	v_fmamk_f32 v32, v29, 0xbf317218, v28
	v_xor_b32_e32 v12, v13, v12
	v_cmp_class_f32_e64 vcc, v14, s3
	v_fmac_f32_e32 v32, 0x3102e308, v29
	global_load_dwordx4 v[16:19], v[36:37], off
	global_load_dwordx4 v[24:27], v[40:41], off
	v_cndmask_b32_e32 v31, v199, v12, vcc
	v_fmamk_f32 v12, v32, 0x395133b1, v193
	v_fmaak_f32 v12, v32, v12, 0x3c0887f9
	v_fmaak_f32 v12, v32, v12, 0x3d2aaa81
	v_fmaak_f32 v12, v32, v12, 0x3e2aaaab
	s_mov_b32 s0, 0x43000000
	v_fma_f32 v12, v32, v12, 0.5
	v_cmp_eq_f32_e32 vcc, s0, v29
	v_ldexp_f32 v29, 1.0, v30
	v_mul_f32_e32 v33, v32, v12
	v_cndmask_b32_e32 v29, v29, v200, vcc
	v_fmac_f32_e32 v32, v32, v33
	v_add_f32_e32 v30, -1.0, v29
	v_fmac_f32_e32 v30, v29, v32
	v_add_f32_e32 v29, v30, v30
	s_mov_b32 s0, 0x42b17217
	v_cndmask_b32_e32 v29, v30, v29, vcc
	v_cmp_nlt_f32_e32 vcc, s0, v28
	s_mov_b32 s0, 0xc1880000
	global_load_dwordx4 v[12:15], v[36:37], off offset:16
	global_load_dwordx4 v[20:23], v[40:41], off offset:16
	v_cndmask_b32_e32 v30, v196, v29, vcc
	v_cmp_ngt_f32_e32 vcc, s0, v28
	v_pk_mul_f32 v[28:29], v[10:11], v[10:11]
	v_xor_b32_e32 v46, v46, v45
	v_add_f32_e32 v38, v28, v29
	v_div_scale_f32 v39, s[0:1], v38, v38, 1.0
	v_rcp_f32_e32 v42, v39
	v_add_f32_e32 v28, v31, v31
	v_mul_f32_e32 v49, v31, v28
	v_cndmask_b32_e32 v48, -1.0, v30, vcc
	v_fma_f32 v28, -v39, v42, 1.0
	v_fmac_f32_e32 v42, v28, v42
	v_div_scale_f32 v43, vcc, 1.0, v38, 1.0
	v_mul_f32_e32 v44, v43, v42
	v_fma_f32 v28, -v39, v44, v43
	v_fmac_f32_e32 v44, v28, v42
	global_load_dwordx4 v[28:31], v[36:37], off offset:32
	global_load_dwordx4 v[32:35], v[40:41], off offset:32
	v_fma_f32 v39, -v39, v44, v43
	v_div_fmas_f32 v39, v39, v42, v44
	v_div_fixup_f32 v44, v39, v38, 1.0
	global_load_dwordx4 v[36:39], v[36:37], off offset:48
	s_nop 0
	global_load_dwordx4 v[40:43], v[40:41], off offset:48
	v_xor_b32_e32 v45, v47, v45
	v_cndmask_b32_e64 v47, v199, v46, s[40:41]
	v_cndmask_b32_e64 v46, v199, v45, s[40:41]
	v_fma_f32 v48, v48, v46, -v49
	v_pk_mul_f32 v[78:79], v[0:1], v[46:47] op_sel_hi:[0,1]
	v_mov_b32_e32 v46, v11
	v_mov_b32_e32 v47, v10
	v_mov_b32_e32 v0, v11
	v_pk_mul_f32 v[10:11], v[46:47], v[48:49] op_sel:[1,0] op_sel_hi:[0,0]
	v_pk_fma_f32 v[48:49], v[0:1], v[78:79], v[10:11] op_sel:[0,1,0]
	v_pk_fma_f32 v[10:11], v[46:47], v[78:79], v[10:11] op_sel:[0,1,0] neg_lo:[0,0,1] neg_hi:[0,0,1]
	s_waitcnt lgkmcnt(0)
	s_add_i32 s0, s68, s24
	v_mov_b32_e32 v49, v11
	v_pk_mul_f32 v[10:11], v[44:45], v[48:49] op_sel_hi:[0,1]
	s_ashr_i32 s1, s0, 31
	s_lshl_b64 s[0:1], s[0:1], 12
	v_mov_b32_e32 v71, v1
	s_waitcnt vmcnt(7)
	v_mov_b32_e32 v44, v16
	s_waitcnt vmcnt(6)
	v_mov_b32_e32 v45, v24
	v_pk_mul_f32 v[44:45], v[44:45], v[10:11]
	s_nop 0
	v_sub_f32_e32 v0, v44, v45
	v_mov_b32_e32 v44, v24
	v_mov_b32_e32 v45, v16
	v_mov_b32_e32 v16, v25
	v_pk_mul_f32 v[44:45], v[44:45], v[10:11]
	v_mov_b32_e32 v24, v17
	v_pk_mul_f32 v[16:17], v[16:17], v[10:11]
	v_add_f32_e32 v46, v44, v45
	v_pk_mul_f32 v[44:45], v[24:25], v[10:11]
	v_add_f32_e32 v25, v16, v17
	v_mov_b32_e32 v16, v18
	v_mov_b32_e32 v17, v26
	v_pk_mul_f32 v[16:17], v[16:17], v[10:11]
	v_sub_f32_e32 v24, v44, v45
	v_sub_f32_e32 v44, v16, v17
	v_mov_b32_e32 v16, v26
	v_mov_b32_e32 v17, v18
	v_pk_mul_f32 v[16:17], v[16:17], v[10:11]
	v_mov_b32_e32 v26, v19
	v_add_f32_e32 v45, v16, v17
	v_pk_mul_f32 v[16:17], v[26:27], v[10:11]
	v_mov_b32_e32 v18, v27
	v_sub_f32_e32 v26, v16, v17
	v_pk_mul_f32 v[16:17], v[18:19], v[10:11]
	s_nop 0
	v_add_f32_e32 v19, v16, v17
	s_waitcnt vmcnt(5)
	v_mov_b32_e32 v16, v12
	s_waitcnt vmcnt(4)
	v_mov_b32_e32 v17, v20
	v_pk_mul_f32 v[16:17], v[16:17], v[10:11]
	s_nop 0
	v_sub_f32_e32 v18, v16, v17
	v_mov_b32_e32 v16, v20
	v_mov_b32_e32 v17, v12
	v_mov_b32_e32 v12, v21
	v_pk_mul_f32 v[16:17], v[16:17], v[10:11]
	v_mov_b32_e32 v20, v13
	v_pk_mul_f32 v[12:13], v[12:13], v[10:11]
	v_add_f32_e32 v27, v16, v17
	v_pk_mul_f32 v[16:17], v[20:21], v[10:11]
	v_add_f32_e32 v20, v12, v13
	v_mov_b32_e32 v12, v14
	v_mov_b32_e32 v13, v22
	v_pk_mul_f32 v[12:13], v[12:13], v[10:11]
	v_sub_f32_e32 v16, v16, v17
	v_sub_f32_e32 v17, v12, v13
	v_mov_b32_e32 v12, v22
	v_mov_b32_e32 v13, v14
	v_pk_mul_f32 v[12:13], v[12:13], v[10:11]
	v_mov_b32_e32 v22, v15
	v_add_f32_e32 v21, v12, v13
	v_pk_mul_f32 v[12:13], v[22:23], v[10:11]
	v_mov_b32_e32 v14, v23
	v_sub_f32_e32 v22, v12, v13
	v_pk_mul_f32 v[12:13], v[14:15], v[10:11]
	s_nop 0
	v_add_f32_e32 v23, v12, v13
	s_waitcnt vmcnt(3)
	v_mov_b32_e32 v12, v28
	s_waitcnt vmcnt(2)
	v_mov_b32_e32 v13, v32
	v_pk_mul_f32 v[12:13], v[12:13], v[10:11]
	s_nop 0
	v_sub_f32_e32 v14, v12, v13
	v_mov_b32_e32 v12, v32
	v_mov_b32_e32 v13, v28
	v_pk_mul_f32 v[12:13], v[12:13], v[10:11]
	v_mov_b32_e32 v32, v29
	v_add_f32_e32 v47, v12, v13
	v_pk_mul_f32 v[12:13], v[32:33], v[10:11]
	v_mov_b32_e32 v28, v33
	v_sub_f32_e32 v15, v12, v13
	v_pk_mul_f32 v[12:13], v[28:29], v[10:11]
	s_nop 0
	v_add_f32_e32 v28, v12, v13
	v_mov_b32_e32 v12, v30
	v_mov_b32_e32 v13, v34
	v_pk_mul_f32 v[12:13], v[12:13], v[10:11]
	s_nop 0
	v_sub_f32_e32 v29, v12, v13
	v_mov_b32_e32 v12, v34
	v_mov_b32_e32 v13, v30
	v_pk_mul_f32 v[12:13], v[12:13], v[10:11]
	v_mov_b32_e32 v34, v31
	v_add_f32_e32 v32, v12, v13
	v_pk_mul_f32 v[12:13], v[34:35], v[10:11]
	v_mov_b32_e32 v30, v35
	v_sub_f32_e32 v33, v12, v13
	v_pk_mul_f32 v[12:13], v[30:31], v[10:11]
	s_nop 0
	v_add_f32_e32 v30, v12, v13
	s_waitcnt vmcnt(1)
	v_mov_b32_e32 v12, v36
	s_waitcnt vmcnt(0)
	v_mov_b32_e32 v13, v40
	v_pk_mul_f32 v[12:13], v[12:13], v[10:11]
	s_nop 0
	v_sub_f32_e32 v31, v12, v13
	v_mov_b32_e32 v12, v40
	v_mov_b32_e32 v13, v36
	v_pk_mul_f32 v[12:13], v[12:13], v[10:11]
	v_mov_b32_e32 v40, v37
	v_add_f32_e32 v34, v12, v13
	v_pk_mul_f32 v[12:13], v[40:41], v[10:11]
	v_mov_b32_e32 v36, v41
	v_sub_f32_e32 v35, v12, v13
	v_pk_mul_f32 v[12:13], v[36:37], v[10:11]
	s_nop 0
	v_add_f32_e32 v36, v12, v13
	v_mov_b32_e32 v12, v38
	v_mov_b32_e32 v13, v42
	v_pk_mul_f32 v[12:13], v[12:13], v[10:11]
	s_nop 0
	v_sub_f32_e32 v37, v12, v13
	v_mov_b32_e32 v12, v42
	v_mov_b32_e32 v13, v38
	v_pk_mul_f32 v[12:13], v[12:13], v[10:11]
	v_mov_b32_e32 v42, v39
	v_mov_b32_e32 v38, v43
	v_add_f32_e32 v40, v12, v13
	v_pk_mul_f32 v[12:13], v[42:43], v[10:11]
	v_pk_mul_f32 v[10:11], v[38:39], v[10:11]
	v_sub_f32_e32 v41, v12, v13
	v_add_f32_e32 v38, v10, v11
	v_cvt_pk_bf16_f32 v10, v0, v24
	v_cvt_pk_bf16_f32 v11, v44, v26
	v_cvt_pk_bf16_f32 v12, v18, v16
	v_cvt_pk_bf16_f32 v13, v17, v22
	v_add_u32_e32 v0, s17, v112
	v_cvt_pk_bf16_f32 v14, v14, v15
	v_cvt_pk_bf16_f32 v15, v29, v33
	v_cvt_pk_bf16_f32 v16, v31, v35
	v_cvt_pk_bf16_f32 v17, v37, v41
	v_cvt_pk_bf16_f32 v18, v46, v25
	v_cvt_pk_bf16_f32 v19, v45, v19
	v_cvt_pk_bf16_f32 v20, v27, v20
	v_cvt_pk_bf16_f32 v21, v21, v23
	v_cvt_pk_bf16_f32 v22, v47, v28
	v_cvt_pk_bf16_f32 v23, v32, v30
	v_cvt_pk_bf16_f32 v24, v34, v36
	v_cvt_pk_bf16_f32 v25, v40, v38
	ds_write_b128 v0, v[10:13] offset:17408
	ds_write_b128 v0, v[14:17] offset:17424
	ds_write_b128 v0, v[18:21] offset:19456
	ds_write_b128 v0, v[22:25] offset:19472
	s_waitcnt lgkmcnt(0)
	ds_read2st64_b64 v[10:13], v113 offset0:34 offset1:35
	ds_read2st64_b64 v[14:17], v113 offset0:36 offset1:37
	ds_read2st64_b64 v[18:21], v113 offset0:38 offset1:39
	ds_read2st64_b64 v[22:25], v113 offset0:40 offset1:41
	s_waitcnt lgkmcnt(0)
	s_load_dwordx4 s[40:43], s[80:81], 0x80
	v_lshl_or_b32 v26, v58, 2, s0
	v_mov_b32_e32 v27, s1
	s_waitcnt lgkmcnt(0)
	v_lshl_add_u64 v[28:29], s[40:41], 0, v[26:27]
	v_lshl_add_u64 v[26:27], s[42:43], 0, v[26:27]
	v_lshl_add_u64 v[44:45], v[26:27], 0, v[70:71]
	v_lshl_add_u64 v[42:43], v[28:29], 0, v[70:71]
	global_load_dwordx4 v[26:29], v[44:45], off
	global_load_dwordx4 v[162:165], v[42:43], off
	global_load_dwordx4 v[30:33], v[44:45], off offset:64
	global_load_dwordx4 v[166:169], v[42:43], off offset:64
	global_load_dwordx4 v[34:37], v[44:45], off offset:128
	global_load_dwordx4 v[170:173], v[42:43], off offset:128
	global_load_dwordx4 v[38:41], v[44:45], off offset:192
	global_load_dwordx4 v[174:177], v[42:43], off offset:192
	s_load_dwordx2 s[0:1], s[80:81], 0x90
	s_waitcnt lgkmcnt(0)
	s_add_u32 s3, s0, s8
	s_addc_u32 s40, s1, s9
	s_lshl_b32 s22, s68, 4
	s_ashr_i32 s23, s22, 31
	s_lshl_b64 s[0:1], s[22:23], 2
	s_add_u32 s0, s3, s0
	s_addc_u32 s1, s40, s1
	s_and_b64 vcc, exec, s[38:39]
	s_waitcnt vmcnt(0)
	v_xor_b32_e32 v0, 0x80000000, v26
	v_cvt_pk_bf16_f32 v26, v162, v0
	v_xor_b32_e32 v0, 0x80000000, v27
	v_cvt_pk_bf16_f32 v27, v163, v0
	v_xor_b32_e32 v0, 0x80000000, v28
	v_cvt_pk_bf16_f32 v28, v164, v0
	v_xor_b32_e32 v0, 0x80000000, v29
	v_cvt_pk_bf16_f32 v29, v165, v0
	v_xor_b32_e32 v0, 0x80000000, v30
	v_cvt_pk_bf16_f32 v30, v166, v0
	v_xor_b32_e32 v0, 0x80000000, v31
	v_cvt_pk_bf16_f32 v31, v167, v0
	v_xor_b32_e32 v0, 0x80000000, v32
	v_cvt_pk_bf16_f32 v32, v168, v0
	v_xor_b32_e32 v0, 0x80000000, v33
	v_cvt_pk_bf16_f32 v33, v169, v0
	v_xor_b32_e32 v0, 0x80000000, v34
	v_cvt_pk_bf16_f32 v34, v170, v0
	v_xor_b32_e32 v0, 0x80000000, v35
	v_cvt_pk_bf16_f32 v35, v171, v0
	v_xor_b32_e32 v0, 0x80000000, v36
	v_cvt_pk_bf16_f32 v36, v172, v0
	v_xor_b32_e32 v0, 0x80000000, v37
	v_cvt_pk_bf16_f32 v37, v173, v0
	v_xor_b32_e32 v0, 0x80000000, v38
	v_cvt_pk_bf16_f32 v38, v174, v0
	v_xor_b32_e32 v0, 0x80000000, v39
	v_cvt_pk_bf16_f32 v39, v175, v0
	v_xor_b32_e32 v0, 0x80000000, v40
	v_cvt_pk_bf16_f32 v40, v176, v0
	v_xor_b32_e32 v0, 0x80000000, v41
	v_cvt_pk_bf16_f32 v41, v177, v0
	global_load_dwordx4 v[42:45], v70, s[0:1]
	s_mov_b64 s[0:1], -1
	s_cbranch_vccnz .LBB0_186
	s_ashr_i32 s69, s68, 31
	s_mov_b64 s[0:1], 0
